# FFN-up epilogue: conv weight / bias loads issued at the top of the epilogue (in flight under the bf16 LDS staging and its barrier) instead of after the barrier with an immediate wait
# speedup vs baseline: 1.0045x; 1.0045x over previous
.LBB0_640:
	s_and_b64 s[2:3], s[8:9], exec
	s_waitcnt vmcnt(0)
	v_readlane_b32 s2, v255, 15
	v_readlane_b32 s4, v255, 19
	v_readlane_b32 s3, v255, 16
	v_readlane_b32 s5, v255, 20
	s_cselect_b32 s42, s2, s4
	v_readlane_b32 s2, v255, 17
	s_cselect_b32 s28, s51, 0
	s_cselect_b32 s29, s52, 0
	s_cselect_b32 s43, s3, s5
	s_cselect_b32 s46, s2, 0
	s_cmp_lt_i32 s44, 4
	s_mov_b64 s[2:3], -1
	s_waitcnt vmcnt(0) lgkmcnt(0)
	s_barrier
	s_cbranch_scc1 .LBB0_1047
	s_cmp_lt_i32 s44, 6
	s_cbranch_scc1 .LBB0_1041
	s_cmp_gt_i32 s44, 6
	s_cbranch_scc0 .LBB0_654
	v_lshlrev_b32_e32 v244, 2, v175
	v_and_b32_e32 v244, 0x7c, v244
	v_lshl_or_b32 v244, s47, 7, v244
	v_lshlrev_b32_e32 v244, 2, v244
	v_readlane_b32 s100, v253, 61
	v_readlane_b32 s101, v253, 62
	s_mul_i32 s32, s28, 0x10800
	s_add_u32 s100, s100, s32
	s_mul_hi_u32 s32, s28, 0x10800
	s_addc_u32 s101, s101, s32
	v_readlane_b32 s4, v253, 63
	v_readlane_b32 s5, v254, 0
	s_mul_i32 s32, s28, 0x5800
	s_add_u32 s4, s4, s32
	s_mul_hi_u32 s32, s28, 0x5800
	s_addc_u32 s5, s5, s32
	v_add_u32_e32 v245, 0x5000, v244
	v_add_u32_e32 v246, 0xb000, v244
	v_add_u32_e32 v247, 0x8000, v244
	v_add_u32_e32 v226, 0xd000, v244
	v_add_u32_e32 v227, 0x2000, v244
	global_load_dwordx4 v[176:179], v244, s[100:101]
	global_load_dwordx4 v[180:183], v245, s[100:101] offset:2048
	global_load_dwordx4 v[184:187], v246, s[100:101]
	global_load_dwordx4 v[200:203], v227, s[100:101] offset:3072
	global_load_dwordx4 v[228:231], v247, s[100:101] offset:1024
	global_load_dwordx4 v[232:235], v226, s[100:101] offset:3072
	global_load_dwordx4 v[236:239], v244, s[4:5]
	global_load_dwordx4 v[240:243], v227, s[4:5] offset:3072
	s_movk_i32 s15, 0x210
	v_lshlrev_b32_e32 v0, 3, v223
	v_mul_lo_u32 v132, v225, s15
	v_cvt_pk_bf16_f32 v131, v128, v129
	v_cvt_pk_bf16_f32 v130, v126, v127
	v_add3_u32 v0, v224, v132, v0
	v_cvt_pk_bf16_f32 v133, v124, v125
	v_cvt_pk_bf16_f32 v132, v122, v123
	ds_write2_b64 v0, v[130:131], v[132:133] offset1:4
	v_cvt_pk_bf16_f32 v131, v120, v121
	v_cvt_pk_bf16_f32 v130, v118, v119
	v_cvt_pk_bf16_f32 v133, v116, v117
	v_cvt_pk_bf16_f32 v132, v114, v115
	ds_write2_b64 v0, v[130:131], v[132:133] offset0:32 offset1:36
	v_cvt_pk_bf16_f32 v131, v112, v113
	v_cvt_pk_bf16_f32 v130, v110, v111
	v_cvt_pk_bf16_f32 v133, v108, v109
	v_cvt_pk_bf16_f32 v132, v106, v107
	v_add_u32_e32 v134, 0x2000, v0
	ds_write2_b64 v134, v[130:131], v[132:133] offset0:32 offset1:36
	v_cvt_pk_bf16_f32 v131, v104, v105
	v_cvt_pk_bf16_f32 v130, v102, v103
	v_cvt_pk_bf16_f32 v133, v100, v101
	v_cvt_pk_bf16_f32 v132, v98, v99
	ds_write2_b64 v134, v[130:131], v[132:133] offset0:64 offset1:68
	v_cvt_pk_bf16_f32 v131, v96, v97
	v_cvt_pk_bf16_f32 v130, v94, v95
	v_cvt_pk_bf16_f32 v133, v92, v93
	v_cvt_pk_bf16_f32 v132, v90, v91
	v_add_u32_e32 v134, 0x4000, v0
	ds_write2_b64 v134, v[130:131], v[132:133] offset0:64 offset1:68
	v_cvt_pk_bf16_f32 v131, v88, v89
	v_cvt_pk_bf16_f32 v130, v86, v87
	v_cvt_pk_bf16_f32 v133, v84, v85
	v_cvt_pk_bf16_f32 v132, v82, v83
	ds_write2_b64 v134, v[130:131], v[132:133] offset0:96 offset1:100
	v_cvt_pk_bf16_f32 v131, v80, v81
	v_cvt_pk_bf16_f32 v130, v78, v79
	v_cvt_pk_bf16_f32 v133, v76, v77
	v_cvt_pk_bf16_f32 v132, v74, v75
	v_add_u32_e32 v134, 0x6000, v0
	ds_write2_b64 v134, v[130:131], v[132:133] offset0:96 offset1:100
	v_cvt_pk_bf16_f32 v131, v72, v73
	v_cvt_pk_bf16_f32 v130, v70, v71
	v_cvt_pk_bf16_f32 v133, v68, v69
	v_cvt_pk_bf16_f32 v132, v66, v67
	ds_write2_b64 v134, v[130:131], v[132:133] offset0:128 offset1:132
	v_cvt_pk_bf16_f32 v131, v64, v65
	v_cvt_pk_bf16_f32 v130, v62, v63
	v_cvt_pk_bf16_f32 v133, v60, v61
	v_cvt_pk_bf16_f32 v132, v58, v59
	v_add_u32_e32 v134, 0x8000, v0
	ds_write2_b64 v134, v[130:131], v[132:133] offset0:128 offset1:132
	v_cvt_pk_bf16_f32 v131, v56, v57
	v_cvt_pk_bf16_f32 v130, v54, v55
	v_cvt_pk_bf16_f32 v133, v52, v53
	v_cvt_pk_bf16_f32 v132, v50, v51
	ds_write2_b64 v134, v[130:131], v[132:133] offset0:160 offset1:164
	v_cvt_pk_bf16_f32 v131, v48, v49
	v_cvt_pk_bf16_f32 v130, v46, v47
	v_cvt_pk_bf16_f32 v133, v44, v45
	v_cvt_pk_bf16_f32 v132, v42, v43
	v_add_u32_e32 v134, 0xa000, v0
	ds_write2_b64 v134, v[130:131], v[132:133] offset0:160 offset1:164
	v_cvt_pk_bf16_f32 v131, v36, v37
	v_cvt_pk_bf16_f32 v130, v34, v35
	v_cvt_pk_bf16_f32 v133, v32, v33
	v_cvt_pk_bf16_f32 v132, v30, v31
	ds_write2_b64 v134, v[130:131], v[132:133] offset0:192 offset1:196
	v_cvt_pk_bf16_f32 v131, v40, v41
	v_cvt_pk_bf16_f32 v130, v38, v39
	v_cvt_pk_bf16_f32 v133, v28, v29
	v_cvt_pk_bf16_f32 v132, v26, v27
	v_add_u32_e32 v134, 0xc000, v0
	ds_write2_b64 v134, v[130:131], v[132:133] offset0:192 offset1:196
	v_cvt_pk_bf16_f32 v131, v24, v25
	v_cvt_pk_bf16_f32 v130, v22, v23
	v_cvt_pk_bf16_f32 v133, v20, v21
	v_cvt_pk_bf16_f32 v132, v18, v19
	ds_write2_b64 v134, v[130:131], v[132:133] offset0:224 offset1:228
	v_cvt_pk_bf16_f32 v131, v16, v17
	v_cvt_pk_bf16_f32 v130, v14, v15
	v_cvt_pk_bf16_f32 v133, v12, v13
	v_cvt_pk_bf16_f32 v132, v10, v11
	v_add_u32_e32 v134, 0xe000, v0
	ds_write2_b64 v134, v[130:131], v[132:133] offset0:224 offset1:228
	v_cvt_pk_bf16_f32 v131, v8, v9
	v_cvt_pk_bf16_f32 v130, v6, v7
	v_cvt_pk_bf16_f32 v133, v4, v5
	v_cvt_pk_bf16_f32 v132, v2, v3
	v_add_u32_e32 v0, 0xe800, v0
	ds_write2_b64 v0, v[130:131], v[132:133] offset1:4
	v_lshlrev_b32_e32 v0, 2, v175
	v_and_b32_e32 v0, 0x7c, v0
	s_mul_i32 s2, s28, 0x10800
	v_readlane_b32 s48, v253, 61
	v_lshl_or_b32 v164, s47, 7, v0
	s_mul_hi_u32 s3, s28, 0x10800
	v_readlane_b32 s49, v253, 62
	s_add_u32 s2, s48, s2
	v_ashrrev_i32_e32 v165, 31, v164
	s_addc_u32 s3, s49, s3
	v_lshlrev_b64 v[130:131], 2, v[164:165]
	v_lshl_add_u64 v[150:151], s[2:3], 0, v[130:131]
	s_movk_i32 s2, 0x5000
	v_add_co_u32_e32 v134, vcc, s2, v150
	s_mov_b32 s2, 0xb000
	s_nop 0
	v_addc_co_u32_e32 v135, vcc, 0, v151, vcc
	v_add_co_u32_e32 v138, vcc, s2, v150
	v_readlane_b32 s50, v253, 63
	s_nop 0
	v_addc_co_u32_e32 v139, vcc, 0, v151, vcc
	v_add_co_u32_e32 v142, vcc, s25, v150
	s_mul_i32 s4, s28, 0x5800
	s_nop 0
	v_addc_co_u32_e32 v143, vcc, 0, v151, vcc
	s_mov_b32 s2, 0x8000
	v_readlane_b32 s51, v254, 0
	s_mul_hi_u32 s5, s28, 0x5800
	s_add_u32 s4, s50, s4
	v_add_co_u32_e32 v146, vcc, s2, v150
	s_addc_u32 s5, s51, s5
	s_nop 0
	v_addc_co_u32_e32 v147, vcc, 0, v151, vcc
	s_mov_b32 s2, 0xd000
	s_waitcnt lgkmcnt(0)
	s_barrier
	v_lshl_add_u64 v[158:159], s[4:5], 0, v[130:131]
	s_waitcnt vmcnt(0)
	v_mov_b64_e32 v[130:131], v[176:177]
	v_mov_b64_e32 v[132:133], v[178:179]
	v_add_co_u32_e32 v150, vcc, s2, v150
	v_mov_b64_e32 v[134:135], v[180:181]
	v_mov_b64_e32 v[136:137], v[182:183]
	s_nop 0
	v_mov_b64_e32 v[138:139], v[184:185]
	v_mov_b64_e32 v[140:141], v[186:187]
	v_addc_co_u32_e32 v151, vcc, 0, v151, vcc
	v_mov_b64_e32 v[142:143], v[200:201]
	v_mov_b64_e32 v[144:145], v[202:203]
	s_nop 0
	v_mov_b64_e32 v[146:147], v[228:229]
	v_mov_b64_e32 v[148:149], v[230:231]
	s_nop 0
	v_mov_b64_e32 v[150:151], v[232:233]
	v_mov_b64_e32 v[152:153], v[234:235]
	s_nop 0
	v_mov_b64_e32 v[154:155], v[236:237]
	v_mov_b64_e32 v[156:157], v[238:239]
	v_add_co_u32_e32 v158, vcc, 0x2000, v158
	v_ashrrev_i32_e32 v0, 5, v175
	s_nop 0
	v_addc_co_u32_e32 v159, vcc, 0, v159, vcc
	v_mov_b64_e32 v[158:159], v[240:241]
	v_mov_b64_e32 v[160:161], v[242:243]
	v_readlane_b32 s2, v252, 32
	v_readlane_b32 s3, v252, 33
	v_mul_lo_u32 v166, v0, s15
	v_and_b32_e32 v167, 31, v175
	s_mov_b32 s14, 0
	v_lshl_add_u64 v[164:165], v[164:165], 1, s[2:3]
	v_lshl_add_u32 v166, v167, 3, v166
	v_add_u32_e32 v167, s40, v0
	s_waitcnt vmcnt(0)
	s_mov_b32 s14, 0x8800
	v_mul_u32_u24_e32 v63, 0x2100, v0
	v_and_b32_e32 v64, 31, v175
	v_lshl_add_u32 v63, v64, 3, v63
	v_lshlrev_b32_e32 v61, 4, v0
	v_add_u32_e32 v61, 1, v61
	v_add_u32_e32 v62, s40, v61
	s_mov_b32 s4, 0x78787879
	v_mul_hi_i32 v60, v62, s4
	v_lshrrev_b32_e32 v64, 31, v60
	v_ashrrev_i32_e32 v60, 11, v60
	v_add_u32_e32 v60, v60, v64
	v_mul_i32_i24_e32 v60, 0x1100, v60
	v_sub_u32_e32 v60, v62, v60
	s_movk_i32 s4, 0x1600
	v_mad_i64_i32 v[58:59], s[4:5], v62, s4, v[164:165]
	v_mov_b32_e32 v56, 0x1600
	v_mov_b32_e32 v57, 0
	ds_read2_b64 v[26:29], v63 offset1:32
	ds_read2_b64 v[68:71], v63 offset0:66 offset1:98
	s_waitcnt lgkmcnt(0)
	v_lshlrev_b32_e32 v2, 16, v26
	v_and_b32_e32 v3, 0xffff0000, v26
	v_lshlrev_b32_e32 v4, 16, v27
	v_and_b32_e32 v5, 0xffff0000, v27
	v_lshlrev_b32_e32 v14, 16, v28
	v_and_b32_e32 v15, 0xffff0000, v28
	v_lshlrev_b32_e32 v16, 16, v29
	v_and_b32_e32 v17, 0xffff0000, v29
	v_lshlrev_b32_e32 v6, 16, v68
	v_and_b32_e32 v7, 0xffff0000, v68
	v_lshlrev_b32_e32 v8, 16, v69
	v_and_b32_e32 v9, 0xffff0000, v69
	v_lshlrev_b32_e32 v18, 16, v70
	v_and_b32_e32 v19, 0xffff0000, v70
	v_lshlrev_b32_e32 v20, 16, v71
	v_and_b32_e32 v21, 0xffff0000, v71
	v_add_u32_e32 v63, 0x420, v63
	v_add_u32_e32 v64, -1, v60
	v_add_u32_e32 v65, 0xfffffeff, v60
	v_cmp_gt_u32_e32 vcc, 0xfef, v65
	s_mov_b64 s[4:5], vcc
	v_cmp_gt_u32_e32 vcc, 0xef, v64
	s_or_b64 s[4:5], s[4:5], vcc
	v_add_u32_e32 v64, 15, v62
	v_cmp_gt_i32_e32 vcc, s14, v64
	s_and_b64 s[4:5], s[4:5], vcc
	s_xor_b64 s[4:5], s[4:5], exec
	s_cmp_eq_u64 s[4:5], 0
	s_cbranch_scc0 .Lconv_slow
	v_cmp_gt_u32_e32 vcc, 15, v0
	s_mov_b32 s6, 0xbfb8aa3b
	ds_read2_b64 v[26:29], v63 offset1:32
	s_waitcnt lgkmcnt(0)
	v_lshlrev_b32_e32 v10, 16, v26
	v_and_b32_e32 v11, 0xffff0000, v26
	v_lshlrev_b32_e32 v12, 16, v27
	v_and_b32_e32 v13, 0xffff0000, v27
	v_lshlrev_b32_e32 v22, 16, v28
	v_and_b32_e32 v23, 0xffff0000, v28
	v_lshlrev_b32_e32 v24, 16, v29
	v_and_b32_e32 v25, 0xffff0000, v29
	v_add_u32_e32 v63, 0x210, v63
	ds_read2_b64 v[26:29], v63 offset1:32
	v_pk_fma_f32 v[30:31], v[146:147], v[18:19], v[158:159]
	v_pk_fma_f32 v[32:33], v[148:149], v[20:21], v[160:161]
	v_pk_fma_f32 v[34:35], v[134:135], v[6:7], v[154:155]
	v_pk_fma_f32 v[36:37], v[136:137], v[8:9], v[156:157]
	v_pk_fma_f32 v[30:31], v[142:143], v[14:15], v[30:31]
	v_pk_fma_f32 v[32:33], v[144:145], v[16:17], v[32:33]
	v_pk_fma_f32 v[34:35], v[130:131], v[2:3], v[34:35]
	v_pk_fma_f32 v[36:37], v[132:133], v[4:5], v[36:37]
	v_pk_fma_f32 v[30:31], v[150:151], v[22:23], v[30:31]
	v_pk_fma_f32 v[32:33], v[152:153], v[24:25], v[32:33]
	v_pk_fma_f32 v[34:35], v[138:139], v[10:11], v[34:35]
	v_pk_fma_f32 v[36:37], v[140:141], v[12:13], v[36:37]
	v_pk_mul_f32 v[42:43], v[30:31], s[6:7] op_sel_hi:[1,0]
	v_pk_mul_f32 v[44:45], v[32:33], s[6:7] op_sel_hi:[1,0]
	v_exp_f32_e32 v42, v42
	v_exp_f32_e32 v43, v43
	v_exp_f32_e32 v44, v44
	v_exp_f32_e32 v45, v45
	v_pk_add_f32 v[42:43], v[42:43], 1.0 op_sel_hi:[1,0]
	v_pk_add_f32 v[44:45], v[44:45], 1.0 op_sel_hi:[1,0]
	v_rcp_f32_e32 v46, v42
	v_rcp_f32_e32 v47, v43
	v_rcp_f32_e32 v48, v44
	v_rcp_f32_e32 v49, v45
	v_pk_mul_f32 v[46:47], v[30:31], v[46:47]
	v_pk_mul_f32 v[48:49], v[32:33], v[48:49]
	v_pk_mul_f32 v[34:35], v[34:35], v[46:47]
	v_pk_mul_f32 v[36:37], v[36:37], v[48:49]
	v_cvt_pk_bf16_f32 v66, v34, v35
	v_cvt_pk_bf16_f32 v67, v36, v37
	global_store_dwordx2 v[58:59], v[66:67], off
	v_lshl_add_u64 v[58:59], v[58:59], 0, v[56:57]
	s_waitcnt lgkmcnt(0)
	v_lshlrev_b32_e32 v2, 16, v26
	v_and_b32_e32 v3, 0xffff0000, v26
	v_lshlrev_b32_e32 v4, 16, v27
	v_and_b32_e32 v5, 0xffff0000, v27
	v_lshlrev_b32_e32 v14, 16, v28
	v_and_b32_e32 v15, 0xffff0000, v28
	v_lshlrev_b32_e32 v16, 16, v29
	v_and_b32_e32 v17, 0xffff0000, v29
	v_add_u32_e32 v63, 0x210, v63
	ds_read2_b64 v[26:29], v63 offset1:32
	v_pk_fma_f32 v[30:31], v[146:147], v[22:23], v[158:159]
	v_pk_fma_f32 v[32:33], v[148:149], v[24:25], v[160:161]
	v_pk_fma_f32 v[34:35], v[134:135], v[10:11], v[154:155]
	v_pk_fma_f32 v[36:37], v[136:137], v[12:13], v[156:157]
	v_pk_fma_f32 v[30:31], v[142:143], v[18:19], v[30:31]
	v_pk_fma_f32 v[32:33], v[144:145], v[20:21], v[32:33]
	v_pk_fma_f32 v[34:35], v[130:131], v[6:7], v[34:35]
	v_pk_fma_f32 v[36:37], v[132:133], v[8:9], v[36:37]
	v_pk_fma_f32 v[30:31], v[150:151], v[14:15], v[30:31]
	v_pk_fma_f32 v[32:33], v[152:153], v[16:17], v[32:33]
	v_pk_fma_f32 v[34:35], v[138:139], v[2:3], v[34:35]
	v_pk_fma_f32 v[36:37], v[140:141], v[4:5], v[36:37]
	v_pk_mul_f32 v[42:43], v[30:31], s[6:7] op_sel_hi:[1,0]
	v_pk_mul_f32 v[44:45], v[32:33], s[6:7] op_sel_hi:[1,0]
	v_exp_f32_e32 v42, v42
	v_exp_f32_e32 v43, v43
	v_exp_f32_e32 v44, v44
	v_exp_f32_e32 v45, v45
	v_pk_add_f32 v[42:43], v[42:43], 1.0 op_sel_hi:[1,0]
	v_pk_add_f32 v[44:45], v[44:45], 1.0 op_sel_hi:[1,0]
	v_rcp_f32_e32 v46, v42
	v_rcp_f32_e32 v47, v43
	v_rcp_f32_e32 v48, v44
	v_rcp_f32_e32 v49, v45
	v_pk_mul_f32 v[46:47], v[30:31], v[46:47]
	v_pk_mul_f32 v[48:49], v[32:33], v[48:49]
	v_pk_mul_f32 v[34:35], v[34:35], v[46:47]
	v_pk_mul_f32 v[36:37], v[36:37], v[48:49]
	v_cvt_pk_bf16_f32 v66, v34, v35
	v_cvt_pk_bf16_f32 v67, v36, v37
	global_store_dwordx2 v[58:59], v[66:67], off
	v_lshl_add_u64 v[58:59], v[58:59], 0, v[56:57]
	s_waitcnt lgkmcnt(0)
	v_lshlrev_b32_e32 v6, 16, v26
	v_and_b32_e32 v7, 0xffff0000, v26
	v_lshlrev_b32_e32 v8, 16, v27
	v_and_b32_e32 v9, 0xffff0000, v27
	v_lshlrev_b32_e32 v18, 16, v28
	v_and_b32_e32 v19, 0xffff0000, v28
	v_lshlrev_b32_e32 v20, 16, v29
	v_and_b32_e32 v21, 0xffff0000, v29
	v_add_u32_e32 v63, 0x210, v63
	ds_read2_b64 v[26:29], v63 offset1:32
	v_pk_fma_f32 v[30:31], v[146:147], v[14:15], v[158:159]
	v_pk_fma_f32 v[32:33], v[148:149], v[16:17], v[160:161]
	v_pk_fma_f32 v[34:35], v[134:135], v[2:3], v[154:155]
	v_pk_fma_f32 v[36:37], v[136:137], v[4:5], v[156:157]
	v_pk_fma_f32 v[30:31], v[142:143], v[22:23], v[30:31]
	v_pk_fma_f32 v[32:33], v[144:145], v[24:25], v[32:33]
	v_pk_fma_f32 v[34:35], v[130:131], v[10:11], v[34:35]
	v_pk_fma_f32 v[36:37], v[132:133], v[12:13], v[36:37]
	v_pk_fma_f32 v[30:31], v[150:151], v[18:19], v[30:31]
	v_pk_fma_f32 v[32:33], v[152:153], v[20:21], v[32:33]
	v_pk_fma_f32 v[34:35], v[138:139], v[6:7], v[34:35]
	v_pk_fma_f32 v[36:37], v[140:141], v[8:9], v[36:37]
	v_pk_mul_f32 v[42:43], v[30:31], s[6:7] op_sel_hi:[1,0]
	v_pk_mul_f32 v[44:45], v[32:33], s[6:7] op_sel_hi:[1,0]
	v_exp_f32_e32 v42, v42
	v_exp_f32_e32 v43, v43
	v_exp_f32_e32 v44, v44
	v_exp_f32_e32 v45, v45
	v_pk_add_f32 v[42:43], v[42:43], 1.0 op_sel_hi:[1,0]
	v_pk_add_f32 v[44:45], v[44:45], 1.0 op_sel_hi:[1,0]
	v_rcp_f32_e32 v46, v42
	v_rcp_f32_e32 v47, v43
	v_rcp_f32_e32 v48, v44
	v_rcp_f32_e32 v49, v45
	v_pk_mul_f32 v[46:47], v[30:31], v[46:47]
	v_pk_mul_f32 v[48:49], v[32:33], v[48:49]
	v_pk_mul_f32 v[34:35], v[34:35], v[46:47]
	v_pk_mul_f32 v[36:37], v[36:37], v[48:49]
	v_cvt_pk_bf16_f32 v66, v34, v35
	v_cvt_pk_bf16_f32 v67, v36, v37
	global_store_dwordx2 v[58:59], v[66:67], off
	v_lshl_add_u64 v[58:59], v[58:59], 0, v[56:57]
	s_waitcnt lgkmcnt(0)
	v_lshlrev_b32_e32 v10, 16, v26
	v_and_b32_e32 v11, 0xffff0000, v26
	v_lshlrev_b32_e32 v12, 16, v27
	v_and_b32_e32 v13, 0xffff0000, v27
	v_lshlrev_b32_e32 v22, 16, v28
	v_and_b32_e32 v23, 0xffff0000, v28
	v_lshlrev_b32_e32 v24, 16, v29
	v_and_b32_e32 v25, 0xffff0000, v29
	v_add_u32_e32 v63, 0x210, v63
	ds_read2_b64 v[26:29], v63 offset1:32
	v_pk_fma_f32 v[30:31], v[146:147], v[18:19], v[158:159]
	v_pk_fma_f32 v[32:33], v[148:149], v[20:21], v[160:161]
	v_pk_fma_f32 v[34:35], v[134:135], v[6:7], v[154:155]
	v_pk_fma_f32 v[36:37], v[136:137], v[8:9], v[156:157]
	v_pk_fma_f32 v[30:31], v[142:143], v[14:15], v[30:31]
	v_pk_fma_f32 v[32:33], v[144:145], v[16:17], v[32:33]
	v_pk_fma_f32 v[34:35], v[130:131], v[2:3], v[34:35]
	v_pk_fma_f32 v[36:37], v[132:133], v[4:5], v[36:37]
	v_pk_fma_f32 v[30:31], v[150:151], v[22:23], v[30:31]
	v_pk_fma_f32 v[32:33], v[152:153], v[24:25], v[32:33]
	v_pk_fma_f32 v[34:35], v[138:139], v[10:11], v[34:35]
	v_pk_fma_f32 v[36:37], v[140:141], v[12:13], v[36:37]
	v_pk_mul_f32 v[42:43], v[30:31], s[6:7] op_sel_hi:[1,0]
	v_pk_mul_f32 v[44:45], v[32:33], s[6:7] op_sel_hi:[1,0]
	v_exp_f32_e32 v42, v42
	v_exp_f32_e32 v43, v43
	v_exp_f32_e32 v44, v44
	v_exp_f32_e32 v45, v45
	v_pk_add_f32 v[42:43], v[42:43], 1.0 op_sel_hi:[1,0]
	v_pk_add_f32 v[44:45], v[44:45], 1.0 op_sel_hi:[1,0]
	v_rcp_f32_e32 v46, v42
	v_rcp_f32_e32 v47, v43
	v_rcp_f32_e32 v48, v44
	v_rcp_f32_e32 v49, v45
	v_pk_mul_f32 v[46:47], v[30:31], v[46:47]
	v_pk_mul_f32 v[48:49], v[32:33], v[48:49]
	v_pk_mul_f32 v[34:35], v[34:35], v[46:47]
	v_pk_mul_f32 v[36:37], v[36:37], v[48:49]
	v_cvt_pk_bf16_f32 v66, v34, v35
	v_cvt_pk_bf16_f32 v67, v36, v37
	global_store_dwordx2 v[58:59], v[66:67], off
	v_lshl_add_u64 v[58:59], v[58:59], 0, v[56:57]
	s_waitcnt lgkmcnt(0)
	v_lshlrev_b32_e32 v2, 16, v26
	v_and_b32_e32 v3, 0xffff0000, v26
	v_lshlrev_b32_e32 v4, 16, v27
	v_and_b32_e32 v5, 0xffff0000, v27
	v_lshlrev_b32_e32 v14, 16, v28
	v_and_b32_e32 v15, 0xffff0000, v28
	v_lshlrev_b32_e32 v16, 16, v29
	v_and_b32_e32 v17, 0xffff0000, v29
	v_add_u32_e32 v63, 0x210, v63
	ds_read2_b64 v[26:29], v63 offset1:32
	v_pk_fma_f32 v[30:31], v[146:147], v[22:23], v[158:159]
	v_pk_fma_f32 v[32:33], v[148:149], v[24:25], v[160:161]
	v_pk_fma_f32 v[34:35], v[134:135], v[10:11], v[154:155]
	v_pk_fma_f32 v[36:37], v[136:137], v[12:13], v[156:157]
	v_pk_fma_f32 v[30:31], v[142:143], v[18:19], v[30:31]
	v_pk_fma_f32 v[32:33], v[144:145], v[20:21], v[32:33]
	v_pk_fma_f32 v[34:35], v[130:131], v[6:7], v[34:35]
	v_pk_fma_f32 v[36:37], v[132:133], v[8:9], v[36:37]
	v_pk_fma_f32 v[30:31], v[150:151], v[14:15], v[30:31]
	v_pk_fma_f32 v[32:33], v[152:153], v[16:17], v[32:33]
	v_pk_fma_f32 v[34:35], v[138:139], v[2:3], v[34:35]
	v_pk_fma_f32 v[36:37], v[140:141], v[4:5], v[36:37]
	v_pk_mul_f32 v[42:43], v[30:31], s[6:7] op_sel_hi:[1,0]
	v_pk_mul_f32 v[44:45], v[32:33], s[6:7] op_sel_hi:[1,0]
	v_exp_f32_e32 v42, v42
	v_exp_f32_e32 v43, v43
	v_exp_f32_e32 v44, v44
	v_exp_f32_e32 v45, v45
	v_pk_add_f32 v[42:43], v[42:43], 1.0 op_sel_hi:[1,0]
	v_pk_add_f32 v[44:45], v[44:45], 1.0 op_sel_hi:[1,0]
	v_rcp_f32_e32 v46, v42
	v_rcp_f32_e32 v47, v43
	v_rcp_f32_e32 v48, v44
	v_rcp_f32_e32 v49, v45
	v_pk_mul_f32 v[46:47], v[30:31], v[46:47]
	v_pk_mul_f32 v[48:49], v[32:33], v[48:49]
	v_pk_mul_f32 v[34:35], v[34:35], v[46:47]
	v_pk_mul_f32 v[36:37], v[36:37], v[48:49]
	v_cvt_pk_bf16_f32 v66, v34, v35
	v_cvt_pk_bf16_f32 v67, v36, v37
	global_store_dwordx2 v[58:59], v[66:67], off
	v_lshl_add_u64 v[58:59], v[58:59], 0, v[56:57]
	s_waitcnt lgkmcnt(0)
	v_lshlrev_b32_e32 v6, 16, v26
	v_and_b32_e32 v7, 0xffff0000, v26
	v_lshlrev_b32_e32 v8, 16, v27
	v_and_b32_e32 v9, 0xffff0000, v27
	v_lshlrev_b32_e32 v18, 16, v28
	v_and_b32_e32 v19, 0xffff0000, v28
	v_lshlrev_b32_e32 v20, 16, v29
	v_and_b32_e32 v21, 0xffff0000, v29
	v_add_u32_e32 v63, 0x210, v63
	ds_read2_b64 v[26:29], v63 offset1:32
	v_pk_fma_f32 v[30:31], v[146:147], v[14:15], v[158:159]
	v_pk_fma_f32 v[32:33], v[148:149], v[16:17], v[160:161]
	v_pk_fma_f32 v[34:35], v[134:135], v[2:3], v[154:155]
	v_pk_fma_f32 v[36:37], v[136:137], v[4:5], v[156:157]
	v_pk_fma_f32 v[30:31], v[142:143], v[22:23], v[30:31]
	v_pk_fma_f32 v[32:33], v[144:145], v[24:25], v[32:33]
	v_pk_fma_f32 v[34:35], v[130:131], v[10:11], v[34:35]
	v_pk_fma_f32 v[36:37], v[132:133], v[12:13], v[36:37]
	v_pk_fma_f32 v[30:31], v[150:151], v[18:19], v[30:31]
	v_pk_fma_f32 v[32:33], v[152:153], v[20:21], v[32:33]
	v_pk_fma_f32 v[34:35], v[138:139], v[6:7], v[34:35]
	v_pk_fma_f32 v[36:37], v[140:141], v[8:9], v[36:37]
	v_pk_mul_f32 v[42:43], v[30:31], s[6:7] op_sel_hi:[1,0]
	v_pk_mul_f32 v[44:45], v[32:33], s[6:7] op_sel_hi:[1,0]
	v_exp_f32_e32 v42, v42
	v_exp_f32_e32 v43, v43
	v_exp_f32_e32 v44, v44
	v_exp_f32_e32 v45, v45
	v_pk_add_f32 v[42:43], v[42:43], 1.0 op_sel_hi:[1,0]
	v_pk_add_f32 v[44:45], v[44:45], 1.0 op_sel_hi:[1,0]
	v_rcp_f32_e32 v46, v42
	v_rcp_f32_e32 v47, v43
	v_rcp_f32_e32 v48, v44
	v_rcp_f32_e32 v49, v45
	v_pk_mul_f32 v[46:47], v[30:31], v[46:47]
	v_pk_mul_f32 v[48:49], v[32:33], v[48:49]
	v_pk_mul_f32 v[34:35], v[34:35], v[46:47]
	v_pk_mul_f32 v[36:37], v[36:37], v[48:49]
	v_cvt_pk_bf16_f32 v66, v34, v35
	v_cvt_pk_bf16_f32 v67, v36, v37
	global_store_dwordx2 v[58:59], v[66:67], off
	v_lshl_add_u64 v[58:59], v[58:59], 0, v[56:57]
	s_waitcnt lgkmcnt(0)
	v_lshlrev_b32_e32 v10, 16, v26
	v_and_b32_e32 v11, 0xffff0000, v26
	v_lshlrev_b32_e32 v12, 16, v27
	v_and_b32_e32 v13, 0xffff0000, v27
	v_lshlrev_b32_e32 v22, 16, v28
	v_and_b32_e32 v23, 0xffff0000, v28
	v_lshlrev_b32_e32 v24, 16, v29
	v_and_b32_e32 v25, 0xffff0000, v29
	v_add_u32_e32 v63, 0x210, v63
	ds_read2_b64 v[26:29], v63 offset1:32
	v_pk_fma_f32 v[30:31], v[146:147], v[18:19], v[158:159]
	v_pk_fma_f32 v[32:33], v[148:149], v[20:21], v[160:161]
	v_pk_fma_f32 v[34:35], v[134:135], v[6:7], v[154:155]
	v_pk_fma_f32 v[36:37], v[136:137], v[8:9], v[156:157]
	v_pk_fma_f32 v[30:31], v[142:143], v[14:15], v[30:31]
	v_pk_fma_f32 v[32:33], v[144:145], v[16:17], v[32:33]
	v_pk_fma_f32 v[34:35], v[130:131], v[2:3], v[34:35]
	v_pk_fma_f32 v[36:37], v[132:133], v[4:5], v[36:37]
	v_pk_fma_f32 v[30:31], v[150:151], v[22:23], v[30:31]
	v_pk_fma_f32 v[32:33], v[152:153], v[24:25], v[32:33]
	v_pk_fma_f32 v[34:35], v[138:139], v[10:11], v[34:35]
	v_pk_fma_f32 v[36:37], v[140:141], v[12:13], v[36:37]
	v_pk_mul_f32 v[42:43], v[30:31], s[6:7] op_sel_hi:[1,0]
	v_pk_mul_f32 v[44:45], v[32:33], s[6:7] op_sel_hi:[1,0]
	v_exp_f32_e32 v42, v42
	v_exp_f32_e32 v43, v43
	v_exp_f32_e32 v44, v44
	v_exp_f32_e32 v45, v45
	v_pk_add_f32 v[42:43], v[42:43], 1.0 op_sel_hi:[1,0]
	v_pk_add_f32 v[44:45], v[44:45], 1.0 op_sel_hi:[1,0]
	v_rcp_f32_e32 v46, v42
	v_rcp_f32_e32 v47, v43
	v_rcp_f32_e32 v48, v44
	v_rcp_f32_e32 v49, v45
	v_pk_mul_f32 v[46:47], v[30:31], v[46:47]
	v_pk_mul_f32 v[48:49], v[32:33], v[48:49]
	v_pk_mul_f32 v[34:35], v[34:35], v[46:47]
	v_pk_mul_f32 v[36:37], v[36:37], v[48:49]
	v_cvt_pk_bf16_f32 v66, v34, v35
	v_cvt_pk_bf16_f32 v67, v36, v37
	global_store_dwordx2 v[58:59], v[66:67], off
	v_lshl_add_u64 v[58:59], v[58:59], 0, v[56:57]
	s_waitcnt lgkmcnt(0)
	v_lshlrev_b32_e32 v2, 16, v26
	v_and_b32_e32 v3, 0xffff0000, v26
	v_lshlrev_b32_e32 v4, 16, v27
	v_and_b32_e32 v5, 0xffff0000, v27
	v_lshlrev_b32_e32 v14, 16, v28
	v_and_b32_e32 v15, 0xffff0000, v28
	v_lshlrev_b32_e32 v16, 16, v29
	v_and_b32_e32 v17, 0xffff0000, v29
	v_add_u32_e32 v63, 0x210, v63
	ds_read2_b64 v[26:29], v63 offset1:32
	v_pk_fma_f32 v[30:31], v[146:147], v[22:23], v[158:159]
	v_pk_fma_f32 v[32:33], v[148:149], v[24:25], v[160:161]
	v_pk_fma_f32 v[34:35], v[134:135], v[10:11], v[154:155]
	v_pk_fma_f32 v[36:37], v[136:137], v[12:13], v[156:157]
	v_pk_fma_f32 v[30:31], v[142:143], v[18:19], v[30:31]
	v_pk_fma_f32 v[32:33], v[144:145], v[20:21], v[32:33]
	v_pk_fma_f32 v[34:35], v[130:131], v[6:7], v[34:35]
	v_pk_fma_f32 v[36:37], v[132:133], v[8:9], v[36:37]
	v_pk_fma_f32 v[30:31], v[150:151], v[14:15], v[30:31]
	v_pk_fma_f32 v[32:33], v[152:153], v[16:17], v[32:33]
	v_pk_fma_f32 v[34:35], v[138:139], v[2:3], v[34:35]
	v_pk_fma_f32 v[36:37], v[140:141], v[4:5], v[36:37]
	v_pk_mul_f32 v[42:43], v[30:31], s[6:7] op_sel_hi:[1,0]
	v_pk_mul_f32 v[44:45], v[32:33], s[6:7] op_sel_hi:[1,0]
	v_exp_f32_e32 v42, v42
	v_exp_f32_e32 v43, v43
	v_exp_f32_e32 v44, v44
	v_exp_f32_e32 v45, v45
	v_pk_add_f32 v[42:43], v[42:43], 1.0 op_sel_hi:[1,0]
	v_pk_add_f32 v[44:45], v[44:45], 1.0 op_sel_hi:[1,0]
	v_rcp_f32_e32 v46, v42
	v_rcp_f32_e32 v47, v43
	v_rcp_f32_e32 v48, v44
	v_rcp_f32_e32 v49, v45
	v_pk_mul_f32 v[46:47], v[30:31], v[46:47]
	v_pk_mul_f32 v[48:49], v[32:33], v[48:49]
	v_pk_mul_f32 v[34:35], v[34:35], v[46:47]
	v_pk_mul_f32 v[36:37], v[36:37], v[48:49]
	v_cvt_pk_bf16_f32 v66, v34, v35
	v_cvt_pk_bf16_f32 v67, v36, v37
	global_store_dwordx2 v[58:59], v[66:67], off
	v_lshl_add_u64 v[58:59], v[58:59], 0, v[56:57]
	s_waitcnt lgkmcnt(0)
	v_lshlrev_b32_e32 v6, 16, v26
	v_and_b32_e32 v7, 0xffff0000, v26
	v_lshlrev_b32_e32 v8, 16, v27
	v_and_b32_e32 v9, 0xffff0000, v27
	v_lshlrev_b32_e32 v18, 16, v28
	v_and_b32_e32 v19, 0xffff0000, v28
	v_lshlrev_b32_e32 v20, 16, v29
	v_and_b32_e32 v21, 0xffff0000, v29
	v_add_u32_e32 v63, 0x210, v63
	ds_read2_b64 v[26:29], v63 offset1:32
	v_pk_fma_f32 v[30:31], v[146:147], v[14:15], v[158:159]
	v_pk_fma_f32 v[32:33], v[148:149], v[16:17], v[160:161]
	v_pk_fma_f32 v[34:35], v[134:135], v[2:3], v[154:155]
	v_pk_fma_f32 v[36:37], v[136:137], v[4:5], v[156:157]
	v_pk_fma_f32 v[30:31], v[142:143], v[22:23], v[30:31]
	v_pk_fma_f32 v[32:33], v[144:145], v[24:25], v[32:33]
	v_pk_fma_f32 v[34:35], v[130:131], v[10:11], v[34:35]
	v_pk_fma_f32 v[36:37], v[132:133], v[12:13], v[36:37]
	v_pk_fma_f32 v[30:31], v[150:151], v[18:19], v[30:31]
	v_pk_fma_f32 v[32:33], v[152:153], v[20:21], v[32:33]
	v_pk_fma_f32 v[34:35], v[138:139], v[6:7], v[34:35]
	v_pk_fma_f32 v[36:37], v[140:141], v[8:9], v[36:37]
	v_pk_mul_f32 v[42:43], v[30:31], s[6:7] op_sel_hi:[1,0]
	v_pk_mul_f32 v[44:45], v[32:33], s[6:7] op_sel_hi:[1,0]
	v_exp_f32_e32 v42, v42
	v_exp_f32_e32 v43, v43
	v_exp_f32_e32 v44, v44
	v_exp_f32_e32 v45, v45
	v_pk_add_f32 v[42:43], v[42:43], 1.0 op_sel_hi:[1,0]
	v_pk_add_f32 v[44:45], v[44:45], 1.0 op_sel_hi:[1,0]
	v_rcp_f32_e32 v46, v42
	v_rcp_f32_e32 v47, v43
	v_rcp_f32_e32 v48, v44
	v_rcp_f32_e32 v49, v45
	v_pk_mul_f32 v[46:47], v[30:31], v[46:47]
	v_pk_mul_f32 v[48:49], v[32:33], v[48:49]
	v_pk_mul_f32 v[34:35], v[34:35], v[46:47]
	v_pk_mul_f32 v[36:37], v[36:37], v[48:49]
	v_cvt_pk_bf16_f32 v66, v34, v35
	v_cvt_pk_bf16_f32 v67, v36, v37
	global_store_dwordx2 v[58:59], v[66:67], off
	v_lshl_add_u64 v[58:59], v[58:59], 0, v[56:57]
	s_waitcnt lgkmcnt(0)
	v_lshlrev_b32_e32 v10, 16, v26
	v_and_b32_e32 v11, 0xffff0000, v26
	v_lshlrev_b32_e32 v12, 16, v27
	v_and_b32_e32 v13, 0xffff0000, v27
	v_lshlrev_b32_e32 v22, 16, v28
	v_and_b32_e32 v23, 0xffff0000, v28
	v_lshlrev_b32_e32 v24, 16, v29
	v_and_b32_e32 v25, 0xffff0000, v29
	v_add_u32_e32 v63, 0x210, v63
	ds_read2_b64 v[26:29], v63 offset1:32
	v_pk_fma_f32 v[30:31], v[146:147], v[18:19], v[158:159]
	v_pk_fma_f32 v[32:33], v[148:149], v[20:21], v[160:161]
	v_pk_fma_f32 v[34:35], v[134:135], v[6:7], v[154:155]
	v_pk_fma_f32 v[36:37], v[136:137], v[8:9], v[156:157]
	v_pk_fma_f32 v[30:31], v[142:143], v[14:15], v[30:31]
	v_pk_fma_f32 v[32:33], v[144:145], v[16:17], v[32:33]
	v_pk_fma_f32 v[34:35], v[130:131], v[2:3], v[34:35]
	v_pk_fma_f32 v[36:37], v[132:133], v[4:5], v[36:37]
	v_pk_fma_f32 v[30:31], v[150:151], v[22:23], v[30:31]
	v_pk_fma_f32 v[32:33], v[152:153], v[24:25], v[32:33]
	v_pk_fma_f32 v[34:35], v[138:139], v[10:11], v[34:35]
	v_pk_fma_f32 v[36:37], v[140:141], v[12:13], v[36:37]
	v_pk_mul_f32 v[42:43], v[30:31], s[6:7] op_sel_hi:[1,0]
	v_pk_mul_f32 v[44:45], v[32:33], s[6:7] op_sel_hi:[1,0]
	v_exp_f32_e32 v42, v42
	v_exp_f32_e32 v43, v43
	v_exp_f32_e32 v44, v44
	v_exp_f32_e32 v45, v45
	v_pk_add_f32 v[42:43], v[42:43], 1.0 op_sel_hi:[1,0]
	v_pk_add_f32 v[44:45], v[44:45], 1.0 op_sel_hi:[1,0]
	v_rcp_f32_e32 v46, v42
	v_rcp_f32_e32 v47, v43
	v_rcp_f32_e32 v48, v44
	v_rcp_f32_e32 v49, v45
	v_pk_mul_f32 v[46:47], v[30:31], v[46:47]
	v_pk_mul_f32 v[48:49], v[32:33], v[48:49]
	v_pk_mul_f32 v[34:35], v[34:35], v[46:47]
	v_pk_mul_f32 v[36:37], v[36:37], v[48:49]
	v_cvt_pk_bf16_f32 v66, v34, v35
	v_cvt_pk_bf16_f32 v67, v36, v37
	global_store_dwordx2 v[58:59], v[66:67], off
	v_lshl_add_u64 v[58:59], v[58:59], 0, v[56:57]
	s_waitcnt lgkmcnt(0)
	v_lshlrev_b32_e32 v2, 16, v26
	v_and_b32_e32 v3, 0xffff0000, v26
	v_lshlrev_b32_e32 v4, 16, v27
	v_and_b32_e32 v5, 0xffff0000, v27
	v_lshlrev_b32_e32 v14, 16, v28
	v_and_b32_e32 v15, 0xffff0000, v28
	v_lshlrev_b32_e32 v16, 16, v29
	v_and_b32_e32 v17, 0xffff0000, v29
	v_add_u32_e32 v63, 0x210, v63
	ds_read2_b64 v[26:29], v63 offset1:32
	v_pk_fma_f32 v[30:31], v[146:147], v[22:23], v[158:159]
	v_pk_fma_f32 v[32:33], v[148:149], v[24:25], v[160:161]
	v_pk_fma_f32 v[34:35], v[134:135], v[10:11], v[154:155]
	v_pk_fma_f32 v[36:37], v[136:137], v[12:13], v[156:157]
	v_pk_fma_f32 v[30:31], v[142:143], v[18:19], v[30:31]
	v_pk_fma_f32 v[32:33], v[144:145], v[20:21], v[32:33]
	v_pk_fma_f32 v[34:35], v[130:131], v[6:7], v[34:35]
	v_pk_fma_f32 v[36:37], v[132:133], v[8:9], v[36:37]
	v_pk_fma_f32 v[30:31], v[150:151], v[14:15], v[30:31]
	v_pk_fma_f32 v[32:33], v[152:153], v[16:17], v[32:33]
	v_pk_fma_f32 v[34:35], v[138:139], v[2:3], v[34:35]
	v_pk_fma_f32 v[36:37], v[140:141], v[4:5], v[36:37]
	v_pk_mul_f32 v[42:43], v[30:31], s[6:7] op_sel_hi:[1,0]
	v_pk_mul_f32 v[44:45], v[32:33], s[6:7] op_sel_hi:[1,0]
	v_exp_f32_e32 v42, v42
	v_exp_f32_e32 v43, v43
	v_exp_f32_e32 v44, v44
	v_exp_f32_e32 v45, v45
	v_pk_add_f32 v[42:43], v[42:43], 1.0 op_sel_hi:[1,0]
	v_pk_add_f32 v[44:45], v[44:45], 1.0 op_sel_hi:[1,0]
	v_rcp_f32_e32 v46, v42
	v_rcp_f32_e32 v47, v43
	v_rcp_f32_e32 v48, v44
	v_rcp_f32_e32 v49, v45
	v_pk_mul_f32 v[46:47], v[30:31], v[46:47]
	v_pk_mul_f32 v[48:49], v[32:33], v[48:49]
	v_pk_mul_f32 v[34:35], v[34:35], v[46:47]
	v_pk_mul_f32 v[36:37], v[36:37], v[48:49]
	v_cvt_pk_bf16_f32 v66, v34, v35
	v_cvt_pk_bf16_f32 v67, v36, v37
	global_store_dwordx2 v[58:59], v[66:67], off
	v_lshl_add_u64 v[58:59], v[58:59], 0, v[56:57]
	s_waitcnt lgkmcnt(0)
	v_lshlrev_b32_e32 v6, 16, v26
	v_and_b32_e32 v7, 0xffff0000, v26
	v_lshlrev_b32_e32 v8, 16, v27
	v_and_b32_e32 v9, 0xffff0000, v27
	v_lshlrev_b32_e32 v18, 16, v28
	v_and_b32_e32 v19, 0xffff0000, v28
	v_lshlrev_b32_e32 v20, 16, v29
	v_and_b32_e32 v21, 0xffff0000, v29
	v_add_u32_e32 v63, 0x210, v63
	ds_read2_b64 v[26:29], v63 offset1:32
	v_pk_fma_f32 v[30:31], v[146:147], v[14:15], v[158:159]
	v_pk_fma_f32 v[32:33], v[148:149], v[16:17], v[160:161]
	v_pk_fma_f32 v[34:35], v[134:135], v[2:3], v[154:155]
	v_pk_fma_f32 v[36:37], v[136:137], v[4:5], v[156:157]
	v_pk_fma_f32 v[30:31], v[142:143], v[22:23], v[30:31]
	v_pk_fma_f32 v[32:33], v[144:145], v[24:25], v[32:33]
	v_pk_fma_f32 v[34:35], v[130:131], v[10:11], v[34:35]
	v_pk_fma_f32 v[36:37], v[132:133], v[12:13], v[36:37]
	v_pk_fma_f32 v[30:31], v[150:151], v[18:19], v[30:31]
	v_pk_fma_f32 v[32:33], v[152:153], v[20:21], v[32:33]
	v_pk_fma_f32 v[34:35], v[138:139], v[6:7], v[34:35]
	v_pk_fma_f32 v[36:37], v[140:141], v[8:9], v[36:37]
	v_pk_mul_f32 v[42:43], v[30:31], s[6:7] op_sel_hi:[1,0]
	v_pk_mul_f32 v[44:45], v[32:33], s[6:7] op_sel_hi:[1,0]
	v_exp_f32_e32 v42, v42
	v_exp_f32_e32 v43, v43
	v_exp_f32_e32 v44, v44
	v_exp_f32_e32 v45, v45
	v_pk_add_f32 v[42:43], v[42:43], 1.0 op_sel_hi:[1,0]
	v_pk_add_f32 v[44:45], v[44:45], 1.0 op_sel_hi:[1,0]
	v_rcp_f32_e32 v46, v42
	v_rcp_f32_e32 v47, v43
	v_rcp_f32_e32 v48, v44
	v_rcp_f32_e32 v49, v45
	v_pk_mul_f32 v[46:47], v[30:31], v[46:47]
	v_pk_mul_f32 v[48:49], v[32:33], v[48:49]
	v_pk_mul_f32 v[34:35], v[34:35], v[46:47]
	v_pk_mul_f32 v[36:37], v[36:37], v[48:49]
	v_cvt_pk_bf16_f32 v66, v34, v35
	v_cvt_pk_bf16_f32 v67, v36, v37
	global_store_dwordx2 v[58:59], v[66:67], off
	v_lshl_add_u64 v[58:59], v[58:59], 0, v[56:57]
	s_waitcnt lgkmcnt(0)
	v_lshlrev_b32_e32 v10, 16, v26
	v_and_b32_e32 v11, 0xffff0000, v26
	v_lshlrev_b32_e32 v12, 16, v27
	v_and_b32_e32 v13, 0xffff0000, v27
	v_lshlrev_b32_e32 v22, 16, v28
	v_and_b32_e32 v23, 0xffff0000, v28
	v_lshlrev_b32_e32 v24, 16, v29
	v_and_b32_e32 v25, 0xffff0000, v29
	v_add_u32_e32 v63, 0x210, v63
	ds_read2_b64 v[26:29], v63 offset1:32
	v_pk_fma_f32 v[30:31], v[146:147], v[18:19], v[158:159]
	v_pk_fma_f32 v[32:33], v[148:149], v[20:21], v[160:161]
	v_pk_fma_f32 v[34:35], v[134:135], v[6:7], v[154:155]
	v_pk_fma_f32 v[36:37], v[136:137], v[8:9], v[156:157]
	v_pk_fma_f32 v[30:31], v[142:143], v[14:15], v[30:31]
	v_pk_fma_f32 v[32:33], v[144:145], v[16:17], v[32:33]
	v_pk_fma_f32 v[34:35], v[130:131], v[2:3], v[34:35]
	v_pk_fma_f32 v[36:37], v[132:133], v[4:5], v[36:37]
	v_pk_fma_f32 v[30:31], v[150:151], v[22:23], v[30:31]
	v_pk_fma_f32 v[32:33], v[152:153], v[24:25], v[32:33]
	v_pk_fma_f32 v[34:35], v[138:139], v[10:11], v[34:35]
	v_pk_fma_f32 v[36:37], v[140:141], v[12:13], v[36:37]
	v_pk_mul_f32 v[42:43], v[30:31], s[6:7] op_sel_hi:[1,0]
	v_pk_mul_f32 v[44:45], v[32:33], s[6:7] op_sel_hi:[1,0]
	v_exp_f32_e32 v42, v42
	v_exp_f32_e32 v43, v43
	v_exp_f32_e32 v44, v44
	v_exp_f32_e32 v45, v45
	v_pk_add_f32 v[42:43], v[42:43], 1.0 op_sel_hi:[1,0]
	v_pk_add_f32 v[44:45], v[44:45], 1.0 op_sel_hi:[1,0]
	v_rcp_f32_e32 v46, v42
	v_rcp_f32_e32 v47, v43
	v_rcp_f32_e32 v48, v44
	v_rcp_f32_e32 v49, v45
	v_pk_mul_f32 v[46:47], v[30:31], v[46:47]
	v_pk_mul_f32 v[48:49], v[32:33], v[48:49]
	v_pk_mul_f32 v[34:35], v[34:35], v[46:47]
	v_pk_mul_f32 v[36:37], v[36:37], v[48:49]
	v_cvt_pk_bf16_f32 v66, v34, v35
	v_cvt_pk_bf16_f32 v67, v36, v37
	global_store_dwordx2 v[58:59], v[66:67], off
	v_lshl_add_u64 v[58:59], v[58:59], 0, v[56:57]
	s_waitcnt lgkmcnt(0)
	v_lshlrev_b32_e32 v2, 16, v26
	v_and_b32_e32 v3, 0xffff0000, v26
	v_lshlrev_b32_e32 v4, 16, v27
	v_and_b32_e32 v5, 0xffff0000, v27
	v_lshlrev_b32_e32 v14, 16, v28
	v_and_b32_e32 v15, 0xffff0000, v28
	v_lshlrev_b32_e32 v16, 16, v29
	v_and_b32_e32 v17, 0xffff0000, v29
	v_add_u32_e32 v63, 0x210, v63
	ds_read2_b64 v[26:29], v63 offset1:32
	v_pk_fma_f32 v[30:31], v[146:147], v[22:23], v[158:159]
	v_pk_fma_f32 v[32:33], v[148:149], v[24:25], v[160:161]
	v_pk_fma_f32 v[34:35], v[134:135], v[10:11], v[154:155]
	v_pk_fma_f32 v[36:37], v[136:137], v[12:13], v[156:157]
	v_pk_fma_f32 v[30:31], v[142:143], v[18:19], v[30:31]
	v_pk_fma_f32 v[32:33], v[144:145], v[20:21], v[32:33]
	v_pk_fma_f32 v[34:35], v[130:131], v[6:7], v[34:35]
	v_pk_fma_f32 v[36:37], v[132:133], v[8:9], v[36:37]
	v_pk_fma_f32 v[30:31], v[150:151], v[14:15], v[30:31]
	v_pk_fma_f32 v[32:33], v[152:153], v[16:17], v[32:33]
	v_pk_fma_f32 v[34:35], v[138:139], v[2:3], v[34:35]
	v_pk_fma_f32 v[36:37], v[140:141], v[4:5], v[36:37]
	v_pk_mul_f32 v[42:43], v[30:31], s[6:7] op_sel_hi:[1,0]
	v_pk_mul_f32 v[44:45], v[32:33], s[6:7] op_sel_hi:[1,0]
	v_exp_f32_e32 v42, v42
	v_exp_f32_e32 v43, v43
	v_exp_f32_e32 v44, v44
	v_exp_f32_e32 v45, v45
	v_pk_add_f32 v[42:43], v[42:43], 1.0 op_sel_hi:[1,0]
	v_pk_add_f32 v[44:45], v[44:45], 1.0 op_sel_hi:[1,0]
	v_rcp_f32_e32 v46, v42
	v_rcp_f32_e32 v47, v43
	v_rcp_f32_e32 v48, v44
	v_rcp_f32_e32 v49, v45
	v_pk_mul_f32 v[46:47], v[30:31], v[46:47]
	v_pk_mul_f32 v[48:49], v[32:33], v[48:49]
	v_pk_mul_f32 v[34:35], v[34:35], v[46:47]
	v_pk_mul_f32 v[36:37], v[36:37], v[48:49]
	v_cvt_pk_bf16_f32 v66, v34, v35
	v_cvt_pk_bf16_f32 v67, v36, v37
	global_store_dwordx2 v[58:59], v[66:67], off
	v_lshl_add_u64 v[58:59], v[58:59], 0, v[56:57]
	s_waitcnt lgkmcnt(0)
	v_lshlrev_b32_e32 v6, 16, v26
	v_and_b32_e32 v7, 0xffff0000, v26
	v_lshlrev_b32_e32 v8, 16, v27
	v_and_b32_e32 v9, 0xffff0000, v27
	v_lshlrev_b32_e32 v18, 16, v28
	v_and_b32_e32 v19, 0xffff0000, v28
	v_lshlrev_b32_e32 v20, 16, v29
	v_and_b32_e32 v21, 0xffff0000, v29
	v_add_u32_e32 v63, 0x210, v63
	ds_read2_b64 v[26:29], v63 offset1:32
	v_pk_fma_f32 v[30:31], v[146:147], v[14:15], v[158:159]
	v_pk_fma_f32 v[32:33], v[148:149], v[16:17], v[160:161]
	v_pk_fma_f32 v[34:35], v[134:135], v[2:3], v[154:155]
	v_pk_fma_f32 v[36:37], v[136:137], v[4:5], v[156:157]
	v_pk_fma_f32 v[30:31], v[142:143], v[22:23], v[30:31]
	v_pk_fma_f32 v[32:33], v[144:145], v[24:25], v[32:33]
	v_pk_fma_f32 v[34:35], v[130:131], v[10:11], v[34:35]
	v_pk_fma_f32 v[36:37], v[132:133], v[12:13], v[36:37]
	v_pk_fma_f32 v[30:31], v[150:151], v[18:19], v[30:31]
	v_pk_fma_f32 v[32:33], v[152:153], v[20:21], v[32:33]
	v_pk_fma_f32 v[34:35], v[138:139], v[6:7], v[34:35]
	v_pk_fma_f32 v[36:37], v[140:141], v[8:9], v[36:37]
	v_pk_mul_f32 v[42:43], v[30:31], s[6:7] op_sel_hi:[1,0]
	v_pk_mul_f32 v[44:45], v[32:33], s[6:7] op_sel_hi:[1,0]
	v_exp_f32_e32 v42, v42
	v_exp_f32_e32 v43, v43
	v_exp_f32_e32 v44, v44
	v_exp_f32_e32 v45, v45
	v_pk_add_f32 v[42:43], v[42:43], 1.0 op_sel_hi:[1,0]
	v_pk_add_f32 v[44:45], v[44:45], 1.0 op_sel_hi:[1,0]
	v_rcp_f32_e32 v46, v42
	v_rcp_f32_e32 v47, v43
	v_rcp_f32_e32 v48, v44
	v_rcp_f32_e32 v49, v45
	v_pk_mul_f32 v[46:47], v[30:31], v[46:47]
	v_pk_mul_f32 v[48:49], v[32:33], v[48:49]
	v_pk_mul_f32 v[34:35], v[34:35], v[46:47]
	v_pk_mul_f32 v[36:37], v[36:37], v[48:49]
	v_cvt_pk_bf16_f32 v66, v34, v35
	v_cvt_pk_bf16_f32 v67, v36, v37
	s_and_saveexec_b64 s[4:5], vcc
	global_store_dwordx2 v[58:59], v[66:67], off
	s_or_b64 exec, exec, s[4:5]
	v_lshl_add_u64 v[58:59], v[58:59], 0, v[56:57]
	s_waitcnt lgkmcnt(0)
	v_lshlrev_b32_e32 v10, 16, v26
	v_and_b32_e32 v11, 0xffff0000, v26
	v_lshlrev_b32_e32 v12, 16, v27
	v_and_b32_e32 v13, 0xffff0000, v27
	v_lshlrev_b32_e32 v22, 16, v28
	v_and_b32_e32 v23, 0xffff0000, v28
	v_lshlrev_b32_e32 v24, 16, v29
	v_and_b32_e32 v25, 0xffff0000, v29
	v_pk_fma_f32 v[30:31], v[146:147], v[18:19], v[158:159]
	v_pk_fma_f32 v[32:33], v[148:149], v[20:21], v[160:161]
	v_pk_fma_f32 v[34:35], v[134:135], v[6:7], v[154:155]
	v_pk_fma_f32 v[36:37], v[136:137], v[8:9], v[156:157]
	v_pk_fma_f32 v[30:31], v[142:143], v[14:15], v[30:31]
	v_pk_fma_f32 v[32:33], v[144:145], v[16:17], v[32:33]
	v_pk_fma_f32 v[34:35], v[130:131], v[2:3], v[34:35]
	v_pk_fma_f32 v[36:37], v[132:133], v[4:5], v[36:37]
	v_pk_fma_f32 v[30:31], v[150:151], v[22:23], v[30:31]
	v_pk_fma_f32 v[32:33], v[152:153], v[24:25], v[32:33]
	v_pk_fma_f32 v[34:35], v[138:139], v[10:11], v[34:35]
	v_pk_fma_f32 v[36:37], v[140:141], v[12:13], v[36:37]
	v_pk_mul_f32 v[42:43], v[30:31], s[6:7] op_sel_hi:[1,0]
	v_pk_mul_f32 v[44:45], v[32:33], s[6:7] op_sel_hi:[1,0]
	v_exp_f32_e32 v42, v42
	v_exp_f32_e32 v43, v43
	v_exp_f32_e32 v44, v44
	v_exp_f32_e32 v45, v45
	v_pk_add_f32 v[42:43], v[42:43], 1.0 op_sel_hi:[1,0]
	v_pk_add_f32 v[44:45], v[44:45], 1.0 op_sel_hi:[1,0]
	v_rcp_f32_e32 v46, v42
	v_rcp_f32_e32 v47, v43
	v_rcp_f32_e32 v48, v44
	v_rcp_f32_e32 v49, v45
	v_pk_mul_f32 v[46:47], v[30:31], v[46:47]
	v_pk_mul_f32 v[48:49], v[32:33], v[48:49]
	v_pk_mul_f32 v[34:35], v[34:35], v[46:47]
	v_pk_mul_f32 v[36:37], v[36:37], v[48:49]
	v_cvt_pk_bf16_f32 v66, v34, v35
	v_cvt_pk_bf16_f32 v67, v36, v37
	s_and_saveexec_b64 s[4:5], vcc
	global_store_dwordx2 v[58:59], v[66:67], off
	s_or_b64 exec, exec, s[4:5]
	v_lshl_add_u64 v[58:59], v[58:59], 0, v[56:57]
	s_branch .Lconv_done
